# diff attention loops (both maps) hand-scheduled like MLA: 32-key block pipeline, DMA interleaved
# speedup vs baseline: 1.0169x; 1.0169x over previous
; #define LAS __attribute__((address_space(3)))
; #define MFMA32(a, b, c) __builtin_amdgcn_mfma_f32_32x32x16_bf16((a), (b), (c), 0, 0, 0)
; template <int DQK, int DV, int KSTR, int VSTR>
; DI void attn_step2(const LAS unsigned char* ta, const LAS unsigned char* tb, int koff, int voff, const bf16x8 (&qf)[DQK / 16], f32x16 (&o)[DV / 32], float& l0, float& l1, float& l2, float& l3) {
;     ...
;     f32x16 sa[2], sb[2]; f32x16 zero16;
; #pragma unroll
;     for (int i = 0; i < 16; ++i) zero16[i] = 0.f;
; #pragma unroll
;     for (int ks = 0; ks < NKS; ++ks) {
;         const bf16x8 k0 = *(const LAS bf16x8*)(ta + koff + ks * 32), k1 = *(const LAS bf16x8*)(ta + koff + 32 * KSTR + ks * 32);
;         sa[0] = MFMA32(k0, qf[ks], ks == 0 ? zero16 : sa[0]); sa[1] = MFMA32(k1, qf[ks], ks == 0 ? zero16 : sa[1]);
;     }
;     const unsigned va = (unsigned)(uintptr_t)(ta + voff), vb = (unsigned)(uintptr_t)(tb + voff);
;     s16x4 alo[ND], ahi[ND], blo[ND], bhi[ND];
;     ...
;     VTR_SET(alo, ahi, va, 0);
;     bf16x8 pfa[4], pfb[4];
; #pragma unroll
;     for (int c = 0; c < 4; ++c) {
; #pragma unroll
;         for (int ks = (c * NKS) / 4; ks < ((c + 1) * NKS) / 4; ++ks) {
;             const bf16x8 k0 = *(const LAS bf16x8*)(tb + koff + ks * 32), k1 = *(const LAS bf16x8*)(tb + koff + 32 * KSTR + ks * 32);
;             sb[0] = MFMA32(k0, qf[ks], ks == 0 ? zero16 : sb[0]); sb[1] = MFMA32(k1, qf[ks], ks == 0 ? zero16 : sb[1]);
;         }
;         SM_CHUNK(sa, pfa[c], c);
;     }
;     vtr_wait<ND>(alo, ahi); VTR_SET(blo, bhi, va, 1); PV_MMA(alo, ahi, pfa[0]); SM_CHUNK(sb, pfb[0], 0);
;     vtr_wait<ND>(blo, bhi); VTR_SET(alo, ahi, va, 2); PV_MMA(blo, bhi, pfa[1]); SM_CHUNK(sb, pfb[1], 1);
;     vtr_wait<ND>(alo, ahi); VTR_SET(blo, bhi, va, 3); PV_MMA(alo, ahi, pfa[2]); SM_CHUNK(sb, pfb[2], 2);
;     vtr_wait<ND>(blo, bhi); VTR_SET(alo, ahi, vb, 0); PV_MMA(blo, bhi, pfa[3]); SM_CHUNK(sb, pfb[3], 3);
;     vtr_wait<ND>(alo, ahi); VTR_SET(blo, bhi, vb, 1); PV_MMA(alo, ahi, pfb[0]);
;     vtr_wait<ND>(blo, bhi); VTR_SET(alo, ahi, vb, 2); PV_MMA(blo, bhi, pfb[1]);
;     vtr_wait<ND>(alo, ahi); VTR_SET(blo, bhi, vb, 3); PV_MMA(alo, ahi, pfb[2]);
;     vtr_wait<ND>(blo, bhi); PV_MMA(blo, bhi, pfb[3]);
.LBB0_1824:
	s_and_b32 s10, s26, 0x10000
	v_add_u32_e32 v176, s10, v197
	v_add_u32_e32 v201, s10, v209
	v_add_u32_e32 v201, 0x2400, v201
	s_and_b32 s27, s25, 0x10000
	s_cmp_eq_u32 s26, 0xf0000
	s_cselect_b64 s[44:45], -1, 0
	ds_read_b128 v[212:215], v176
	ds_read_b128 v[216:219], v176 offset:32
	ds_read_b128 v[220:223], v176 offset:64
	ds_read_b128 v[224:227], v176 offset:96
	ds_read_b128 v[172:175], v176 offset:4608
	ds_read_b128 v[178:181], v176 offset:4640
	s_waitcnt lgkmcnt(5)
	v_mfma_f32_32x32x16_bf16 v[64:79], v[212:215], v[136:139], 0
	ds_read_b128 v[212:215], v176 offset:4672
	s_or_b64 s[10:11], s[44:45], s[0:1]
	s_cbranch_scc1 .Ldiff1_dma_skip_0
	s_add_i32 m0, s27, s22
	s_nop 0
	global_load_lds_dwordx4 v[128:129], off
	v_lshl_add_u64 v[128:129], v[128:129], 0, s[82:83]
.Ldiff1_dma_skip_0:
	s_waitcnt lgkmcnt(5)
	v_mfma_f32_32x32x16_bf16 v[64:79], v[216:219], v[140:143], v[64:79]
	ds_read_b128 v[216:219], v176 offset:4704
	s_or_b64 s[10:11], s[44:45], s[38:39]
	s_cbranch_scc1 .Ldiff1_dma_skip_1
	s_add_i32 m0, s27, s23
	s_nop 0
	global_load_lds_dwordx4 v[130:131], off
	v_lshl_add_u64 v[130:131], v[130:131], 0, s[82:83]
.Ldiff1_dma_skip_1:
	s_waitcnt lgkmcnt(5)
	v_mfma_f32_32x32x16_bf16 v[64:79], v[220:223], v[144:147], v[64:79]
	ds_read_b128 v[220:223], v176 offset:32768
	s_or_b64 s[10:11], s[44:45], s[42:43]
	s_cbranch_scc1 .Ldiff1_dma_skip_2
	s_add_i32 m0, s27, s24
	s_nop 0
	global_load_lds_dwordx4 v[132:133], off
	v_lshl_add_u64 v[132:133], v[132:133], 0, s[82:83]
.Ldiff1_dma_skip_2:
	s_waitcnt lgkmcnt(5)
	v_mfma_f32_32x32x16_bf16 v[64:79], v[224:227], v[148:151], v[64:79]
	ds_read_b128 v[224:227], v176 offset:32800
	s_orn2_b64 s[10:11], s[44:45], s[68:69]
	s_cbranch_scc1 .Ldiff1_dma_skip_3
	s_add_i32 m0, s27, s13
	s_nop 0
	global_load_lds_dwordx4 v[134:135], off
	v_lshl_add_u64 v[134:135], v[134:135], 0, s[82:83]
.Ldiff1_dma_skip_3:
	s_waitcnt lgkmcnt(5)
	v_mfma_f32_32x32x16_bf16 v[80:95], v[172:175], v[136:139], 0
	ds_read_b128 v[172:175], v176 offset:32832
	s_or_b64 s[10:11], s[44:45], s[0:1]
	s_cbranch_scc1 .Ldiff1_dma_skip_4
	s_add_i32 s10, s27, s22
	s_add_i32 m0, s10, 0x8000
	s_nop 0
	global_load_lds_dwordx4 v[128:129], off
	v_lshl_add_u64 v[128:129], v[128:129], 0, s[82:83]
.Ldiff1_dma_skip_4:
	s_waitcnt lgkmcnt(5)
	v_mfma_f32_32x32x16_bf16 v[80:95], v[178:181], v[140:143], v[80:95]
	ds_read_b128 v[178:181], v176 offset:32864
	s_or_b64 s[10:11], s[44:45], s[38:39]
	s_cbranch_scc1 .Ldiff1_dma_skip_5
	s_add_i32 s10, s27, s23
	s_add_i32 m0, s10, 0x8000
	s_nop 0
	global_load_lds_dwordx4 v[130:131], off
	v_lshl_add_u64 v[130:131], v[130:131], 0, s[82:83]
.Ldiff1_dma_skip_5:
	v_exp_f32_e32 v64, v64
	v_exp_f32_e32 v65, v65
	v_exp_f32_e32 v66, v66
	s_waitcnt lgkmcnt(5)
	v_mfma_f32_32x32x16_bf16 v[80:95], v[212:215], v[144:147], v[80:95]
	ds_read_b128 v[212:215], v176 offset:37376
	s_or_b64 s[10:11], s[44:45], s[42:43]
	s_cbranch_scc1 .Ldiff1_dma_skip_6
	s_add_i32 s10, s27, s24
	s_add_i32 m0, s10, 0x8000
	s_nop 0
	global_load_lds_dwordx4 v[132:133], off
	v_lshl_add_u64 v[132:133], v[132:133], 0, s[82:83]
.Ldiff1_dma_skip_6:
	v_exp_f32_e32 v67, v67
	v_exp_f32_e32 v68, v68
	v_exp_f32_e32 v69, v69
	s_waitcnt lgkmcnt(5)
	v_mfma_f32_32x32x16_bf16 v[80:95], v[216:219], v[148:151], v[80:95]
	ds_read_b128 v[216:219], v176 offset:37408
	ds_read_b64_tr_b16 v[112:113], v201
	ds_read_b64_tr_b16 v[114:115], v201 offset:2560
	s_orn2_b64 s[10:11], s[44:45], s[68:69]
	s_cbranch_scc1 .Ldiff1_dma_skip_7
	s_add_i32 s10, s27, s13
	s_add_i32 m0, s10, 0x8000
	s_nop 0
	global_load_lds_dwordx4 v[134:135], off
	v_lshl_add_u64 v[134:135], v[134:135], 0, s[82:83]
.Ldiff1_dma_skip_7:
	v_exp_f32_e32 v70, v70
	v_exp_f32_e32 v71, v71
	v_exp_f32_e32 v72, v72
	s_waitcnt lgkmcnt(7)
	v_mfma_f32_32x32x16_bf16 v[96:111], v[220:223], v[136:139], 0
	ds_read_b128 v[220:223], v176 offset:37440
	ds_read_b64_tr_b16 v[116:117], v201 offset:64
	ds_read_b64_tr_b16 v[118:119], v201 offset:2624
	v_exp_f32_e32 v73, v73
	v_exp_f32_e32 v74, v74
	v_exp_f32_e32 v75, v75
	s_waitcnt lgkmcnt(9)
	v_mfma_f32_32x32x16_bf16 v[96:111], v[224:227], v[140:143], v[96:111]
	ds_read_b128 v[224:227], v176 offset:37472
	ds_read_b64_tr_b16 v[120:121], v201 offset:128
	ds_read_b64_tr_b16 v[122:123], v201 offset:2688
	v_exp_f32_e32 v76, v76
	v_exp_f32_e32 v77, v77
	v_exp_f32_e32 v78, v78
	s_waitcnt lgkmcnt(11)
	v_mfma_f32_32x32x16_bf16 v[96:111], v[172:175], v[144:147], v[96:111]
	ds_read_b64_tr_b16 v[124:125], v201 offset:192
	ds_read_b64_tr_b16 v[126:127], v201 offset:2752
	v_exp_f32_e32 v79, v79
	v_cvt_pk_bf16_f32 v152, v64, v65
	v_cvt_pk_bf16_f32 v153, v66, v67
	v_cvt_pk_bf16_f32 v154, v68, v69
	v_cvt_pk_bf16_f32 v155, v70, v71
	s_waitcnt lgkmcnt(12)
	v_mfma_f32_32x32x16_bf16 v[96:111], v[178:181], v[148:151], v[96:111]
	v_cvt_pk_bf16_f32 v156, v72, v73
	v_cvt_pk_bf16_f32 v157, v74, v75
	v_cvt_pk_bf16_f32 v158, v76, v77
	v_cvt_pk_bf16_f32 v159, v78, v79
	v_exp_f32_e32 v80, v80
	s_waitcnt lgkmcnt(8)
	v_mfma_f32_32x32x16_bf16 v[48:63], v[112:115], v[152:155], v[48:63]
	ds_read_b64_tr_b16 v[112:113], v201 offset:5120
	ds_read_b64_tr_b16 v[114:115], v201 offset:7680
	v_exp_f32_e32 v81, v81
	v_exp_f32_e32 v82, v82
	v_exp_f32_e32 v83, v83
	s_waitcnt lgkmcnt(7)
	v_mfma_f32_32x32x16_bf16 v[32:47], v[116:119], v[152:155], v[32:47]
	ds_read_b64_tr_b16 v[116:117], v201 offset:5184
	ds_read_b64_tr_b16 v[118:119], v201 offset:7744
	v_exp_f32_e32 v84, v84
	v_exp_f32_e32 v85, v85
	v_exp_f32_e32 v86, v86
	s_waitcnt lgkmcnt(6)
	v_mfma_f32_32x32x16_bf16 v[16:31], v[120:123], v[152:155], v[16:31]
	ds_read_b64_tr_b16 v[120:121], v201 offset:5248
	ds_read_b64_tr_b16 v[122:123], v201 offset:7808
	v_exp_f32_e32 v87, v87
	v_exp_f32_e32 v88, v88
	v_exp_f32_e32 v89, v89
	s_waitcnt lgkmcnt(6)
; #define VTR_SET(lo, hi, c) do { _Pragma("unroll") for (int d = 0; d < ND; ++d) { \
;         VTR_ASM(lo[d], va, (32 * ((c) >> 1) + 16 * ((c) & 1)) * VSTR + d * 64); VTR_ASM(hi[d], va, (32 * ((c) >> 1) + 16 * ((c) & 1)) * VSTR + d * 64 + 8 * VSTR); } } while (0)
; #define PV_MMA(lo, hi, c) do { _Pragma("unroll") for (int d = 0; d < ND; ++d) { const bf16x8 vf = __builtin_shufflevector(lo[d], hi[d], 0, 1, 2, 3, 4, 5, 6, 7); o[d] = MFMA32(vf, pf[(c) >> 1][(c) & 1], o[d]); } } while (0)
; #define VTR_SET(lo, hi, base, c) do { _Pragma("unroll") for (int d = 0; d < ND; ++d) { \
;         VTR_ASM(lo[d], base, (32 * ((c) >> 1) + 16 * ((c) & 1)) * VSTR + d * 64); VTR_ASM(hi[d], base, (32 * ((c) >> 1) + 16 * ((c) & 1)) * VSTR + d * 64 + 8 * VSTR); } } while (0)
; #define PV_MMA(lo, hi, pf_) do { _Pragma("unroll") for (int d = 0; d < ND; ++d) { const bf16x8 vf = __builtin_shufflevector(lo[d], hi[d], 0, 1, 2, 3, 4, 5, 6, 7); o[d] = MFMA32(vf, pf_, o[d]); } } while (0)
; template <int DQK, int DV, int KSTR, int VSTR>
; DI void attn_step2(const LAS unsigned char* ta, const LAS unsigned char* tb, int koff, int voff, const bf16x8 (&qf)[DQK / 16], f32x16 (&o)[DV / 32], float& l0, float& l1, float& l2, float& l3) {
;     ...
;         SM_CHUNK(sa, pfa[c], c);
;     }
;     vtr_wait<ND>(alo, ahi); VTR_SET(blo, bhi, va, 1); PV_MMA(alo, ahi, pfa[0]); SM_CHUNK(sb, pfb[0], 0);
;     vtr_wait<ND>(blo, bhi); VTR_SET(alo, ahi, va, 2); PV_MMA(blo, bhi, pfa[1]); SM_CHUNK(sb, pfb[1], 1);
;     vtr_wait<ND>(alo, ahi); VTR_SET(blo, bhi, va, 3); PV_MMA(alo, ahi, pfa[2]); SM_CHUNK(sb, pfb[2], 2);
;     vtr_wait<ND>(blo, bhi); VTR_SET(alo, ahi, vb, 0); PV_MMA(blo, bhi, pfa[3]); SM_CHUNK(sb, pfb[3], 3);
;     vtr_wait<ND>(alo, ahi); VTR_SET(blo, bhi, vb, 1); PV_MMA(alo, ahi, pfb[0]);
;     vtr_wait<ND>(blo, bhi); VTR_SET(alo, ahi, vb, 2); PV_MMA(blo, bhi, pfb[1]);
	v_mfma_f32_32x32x16_bf16 v[0:15], v[124:127], v[152:155], v[0:15]
	ds_read_b64_tr_b16 v[124:125], v201 offset:5312
	ds_read_b64_tr_b16 v[126:127], v201 offset:7872
	v_exp_f32_e32 v90, v90
	v_exp_f32_e32 v91, v91
	v_exp_f32_e32 v92, v92
	s_waitcnt lgkmcnt(6)
	v_mfma_f32_32x32x16_bf16 v[48:63], v[112:115], v[156:159], v[48:63]
	ds_read_b64_tr_b16 v[112:113], v201 offset:10240
	ds_read_b64_tr_b16 v[114:115], v201 offset:12800
	v_exp_f32_e32 v93, v93
	v_exp_f32_e32 v94, v94
	v_exp_f32_e32 v95, v95
	s_waitcnt lgkmcnt(6)
	v_mfma_f32_32x32x16_bf16 v[32:47], v[116:119], v[156:159], v[32:47]
	ds_read_b64_tr_b16 v[116:117], v201 offset:10304
	ds_read_b64_tr_b16 v[118:119], v201 offset:12864
	v_cvt_pk_bf16_f32 v160, v80, v81
	v_cvt_pk_bf16_f32 v161, v82, v83
	v_cvt_pk_bf16_f32 v162, v84, v85
	v_cvt_pk_bf16_f32 v163, v86, v87
	v_cvt_pk_bf16_f32 v164, v88, v89
	v_cvt_pk_bf16_f32 v165, v90, v91
	s_waitcnt lgkmcnt(6)
	v_mfma_f32_32x32x16_bf16 v[16:31], v[120:123], v[156:159], v[16:31]
	ds_read_b64_tr_b16 v[120:121], v201 offset:10368
	ds_read_b64_tr_b16 v[122:123], v201 offset:12928
	v_cvt_pk_bf16_f32 v166, v92, v93
	v_cvt_pk_bf16_f32 v167, v94, v95
	v_exp_f32_e32 v96, v96
	v_exp_f32_e32 v97, v97
	s_waitcnt lgkmcnt(6)
	v_mfma_f32_32x32x16_bf16 v[0:15], v[124:127], v[156:159], v[0:15]
	ds_read_b64_tr_b16 v[124:125], v201 offset:10432
	ds_read_b64_tr_b16 v[126:127], v201 offset:12992
	v_exp_f32_e32 v98, v98
	v_exp_f32_e32 v99, v99
	v_exp_f32_e32 v100, v100
	v_add_f32_e32 v168, v168, v64
	v_add_f32_e32 v169, v169, v65
	v_add_f32_e32 v170, v170, v66
	v_add_f32_e32 v171, v171, v67
	v_add_f32_e32 v168, v168, v68
	v_add_f32_e32 v169, v169, v69
	v_add_f32_e32 v170, v170, v70
	v_add_f32_e32 v171, v171, v71
	v_add_f32_e32 v168, v168, v72
	v_add_f32_e32 v169, v169, v73
	v_add_f32_e32 v170, v170, v74
	v_add_f32_e32 v171, v171, v75
	v_add_f32_e32 v168, v168, v76
	v_add_f32_e32 v169, v169, v77
	v_add_f32_e32 v170, v170, v78
	v_add_f32_e32 v171, v171, v79
	v_mfma_f32_32x32x16_bf16 v[64:79], v[212:215], v[136:139], 0
	v_exp_f32_e32 v101, v101
	v_exp_f32_e32 v102, v102
	v_exp_f32_e32 v103, v103
	v_mfma_f32_32x32x16_bf16 v[64:79], v[216:219], v[140:143], v[64:79]
	v_exp_f32_e32 v104, v104
	v_exp_f32_e32 v105, v105
	v_exp_f32_e32 v106, v106
	v_mfma_f32_32x32x16_bf16 v[64:79], v[220:223], v[144:147], v[64:79]
	v_exp_f32_e32 v107, v107
	v_exp_f32_e32 v108, v108
	v_exp_f32_e32 v109, v109
	v_mfma_f32_32x32x16_bf16 v[64:79], v[224:227], v[148:151], v[64:79]
	v_exp_f32_e32 v110, v110
	v_exp_f32_e32 v111, v111
	v_cvt_pk_bf16_f32 v152, v96, v97
	s_waitcnt lgkmcnt(6)
	v_mfma_f32_32x32x16_bf16 v[48:63], v[112:115], v[160:163], v[48:63]
	ds_read_b64_tr_b16 v[112:113], v201 offset:15360
	ds_read_b64_tr_b16 v[114:115], v201 offset:17920
	v_cvt_pk_bf16_f32 v153, v98, v99
	v_cvt_pk_bf16_f32 v154, v100, v101
	v_cvt_pk_bf16_f32 v155, v102, v103
	v_cvt_pk_bf16_f32 v156, v104, v105
	v_cvt_pk_bf16_f32 v157, v106, v107
	s_waitcnt lgkmcnt(6)
	v_mfma_f32_32x32x16_bf16 v[32:47], v[116:119], v[160:163], v[32:47]
	ds_read_b64_tr_b16 v[116:117], v201 offset:15424
	ds_read_b64_tr_b16 v[118:119], v201 offset:17984
	v_cvt_pk_bf16_f32 v158, v108, v109
	v_cvt_pk_bf16_f32 v159, v110, v111
	v_exp_f32_e32 v64, v64
	v_exp_f32_e32 v65, v65
	s_waitcnt lgkmcnt(6)
	v_mfma_f32_32x32x16_bf16 v[16:31], v[120:123], v[160:163], v[16:31]
	ds_read_b64_tr_b16 v[120:121], v201 offset:15488
	ds_read_b64_tr_b16 v[122:123], v201 offset:18048
	v_exp_f32_e32 v66, v66
	v_exp_f32_e32 v67, v67
	v_exp_f32_e32 v68, v68
	s_waitcnt lgkmcnt(6)
	v_mfma_f32_32x32x16_bf16 v[0:15], v[124:127], v[160:163], v[0:15]
	ds_read_b64_tr_b16 v[124:125], v201 offset:15552
	ds_read_b64_tr_b16 v[126:127], v201 offset:18112
	v_exp_f32_e32 v69, v69
	v_exp_f32_e32 v70, v70
	v_exp_f32_e32 v71, v71
	s_waitcnt lgkmcnt(6)
	v_mfma_f32_32x32x16_bf16 v[48:63], v[112:115], v[164:167], v[48:63]
	ds_read_b64_tr_b16 v[112:113], v201 offset:32768
	ds_read_b64_tr_b16 v[114:115], v201 offset:35328
	v_exp_f32_e32 v72, v72
	v_exp_f32_e32 v73, v73
	v_exp_f32_e32 v74, v74
	s_waitcnt lgkmcnt(6)
	v_mfma_f32_32x32x16_bf16 v[32:47], v[116:119], v[164:167], v[32:47]
	ds_read_b64_tr_b16 v[116:117], v201 offset:32832
	ds_read_b64_tr_b16 v[118:119], v201 offset:35392
	v_exp_f32_e32 v75, v75
	v_exp_f32_e32 v76, v76
	v_exp_f32_e32 v77, v77
	s_waitcnt lgkmcnt(6)
	v_mfma_f32_32x32x16_bf16 v[16:31], v[120:123], v[164:167], v[16:31]
	ds_read_b64_tr_b16 v[120:121], v201 offset:32896
	ds_read_b64_tr_b16 v[122:123], v201 offset:35456
	v_exp_f32_e32 v78, v78
	v_exp_f32_e32 v79, v79
	v_cvt_pk_bf16_f32 v160, v64, v65
	s_waitcnt lgkmcnt(6)
	v_mfma_f32_32x32x16_bf16 v[0:15], v[124:127], v[164:167], v[0:15]
	ds_read_b64_tr_b16 v[124:125], v201 offset:32960
	ds_read_b64_tr_b16 v[126:127], v201 offset:35520
	v_cvt_pk_bf16_f32 v161, v66, v67
	v_cvt_pk_bf16_f32 v162, v68, v69
	v_cvt_pk_bf16_f32 v163, v70, v71
	v_cvt_pk_bf16_f32 v164, v72, v73
	v_cvt_pk_bf16_f32 v165, v74, v75
	s_waitcnt lgkmcnt(6)
; #define LAS __attribute__((address_space(3)))
; #define VTR_SET(lo, hi, c) do { _Pragma("unroll") for (int d = 0; d < ND; ++d) { \
;         VTR_ASM(lo[d], va, (32 * ((c) >> 1) + 16 * ((c) & 1)) * VSTR + d * 64); VTR_ASM(hi[d], va, (32 * ((c) >> 1) + 16 * ((c) & 1)) * VSTR + d * 64 + 8 * VSTR); } } while (0)
; #define PV_MMA(lo, hi, c) do { _Pragma("unroll") for (int d = 0; d < ND; ++d) { const bf16x8 vf = __builtin_shufflevector(lo[d], hi[d], 0, 1, 2, 3, 4, 5, 6, 7); o[d] = MFMA32(vf, pf[(c) >> 1][(c) & 1], o[d]); } } while (0)
; #define VTR_SET(lo, hi, base, c) do { _Pragma("unroll") for (int d = 0; d < ND; ++d) { \
;         VTR_ASM(lo[d], base, (32 * ((c) >> 1) + 16 * ((c) & 1)) * VSTR + d * 64); VTR_ASM(hi[d], base, (32 * ((c) >> 1) + 16 * ((c) & 1)) * VSTR + d * 64 + 8 * VSTR); } } while (0)
; #define PV_MMA(lo, hi, pf_) do { _Pragma("unroll") for (int d = 0; d < ND; ++d) { const bf16x8 vf = __builtin_shufflevector(lo[d], hi[d], 0, 1, 2, 3, 4, 5, 6, 7); o[d] = MFMA32(vf, pf_, o[d]); } } while (0)
; template <int DQK, int DV, int KSTR, int VSTR>
; DI void attn_step2(const LAS unsigned char* ta, const LAS unsigned char* tb, int koff, int voff, const bf16x8 (&qf)[DQK / 16], f32x16 (&o)[DV / 32], float& l0, float& l1, float& l2, float& l3) {
;     ...
;     vtr_wait<ND>(blo, bhi); VTR_SET(alo, ahi, vb, 0); PV_MMA(blo, bhi, pfa[3]); SM_CHUNK(sb, pfb[3], 3);
;     vtr_wait<ND>(alo, ahi); VTR_SET(blo, bhi, vb, 1); PV_MMA(alo, ahi, pfb[0]);
;     vtr_wait<ND>(blo, bhi); VTR_SET(alo, ahi, vb, 2); PV_MMA(blo, bhi, pfb[1]);
;     vtr_wait<ND>(alo, ahi); VTR_SET(blo, bhi, vb, 3); PV_MMA(alo, ahi, pfb[2]);
;     vtr_wait<ND>(blo, bhi); PV_MMA(blo, bhi, pfb[3]);
; template <int DQK, int DV, int kpitch, int vpitch>
; DI void attn_map(LAS unsigned char* lds, const bf16x8 (&qf)[DQK / 16], const bf16* Kg, const bf16* Vg, f32x16 (&o)[DV / 32], float& lsum, int tid, int lane) {
;     ...
;     for (int s = 0; s < NSTEP; ++s) {
;         asm volatile("s_waitcnt vmcnt(0)" ::: "memory");
;         __builtin_amdgcn_s_barrier();
;         asm volatile("" ::: "memory");
;         if (s + 1 < NSTEP) ATT_DMA2((s + 1) & 1);
;         const LAS unsigned char* ta = lds + (s & 1) * 2 * TILE;
;         attn_step2<DQK, DV, KSTR, VSTR>(ta, ta + TILE, koff, voff, qf, o, l0, l1, l2, l3);
;     }
	v_mfma_f32_32x32x16_bf16 v[48:63], v[112:115], v[152:155], v[48:63]
	ds_read_b64_tr_b16 v[112:113], v201 offset:37888
	ds_read_b64_tr_b16 v[114:115], v201 offset:40448
	v_cvt_pk_bf16_f32 v166, v76, v77
	v_cvt_pk_bf16_f32 v167, v78, v79
	v_add_f32_e32 v168, v168, v80
	v_add_f32_e32 v169, v169, v81
	v_add_f32_e32 v170, v170, v82
	s_waitcnt lgkmcnt(6)
	v_mfma_f32_32x32x16_bf16 v[32:47], v[116:119], v[152:155], v[32:47]
	ds_read_b64_tr_b16 v[116:117], v201 offset:37952
	ds_read_b64_tr_b16 v[118:119], v201 offset:40512
	v_add_f32_e32 v171, v171, v83
	v_add_f32_e32 v168, v168, v84
	v_add_f32_e32 v169, v169, v85
	v_add_f32_e32 v170, v170, v86
	v_add_f32_e32 v171, v171, v87
	s_waitcnt lgkmcnt(6)
	v_mfma_f32_32x32x16_bf16 v[16:31], v[120:123], v[152:155], v[16:31]
	ds_read_b64_tr_b16 v[120:121], v201 offset:38016
	ds_read_b64_tr_b16 v[122:123], v201 offset:40576
	v_add_f32_e32 v168, v168, v88
	v_add_f32_e32 v169, v169, v89
	v_add_f32_e32 v170, v170, v90
	v_add_f32_e32 v171, v171, v91
	v_add_f32_e32 v168, v168, v92
	s_waitcnt lgkmcnt(6)
	v_mfma_f32_32x32x16_bf16 v[0:15], v[124:127], v[152:155], v[0:15]
	ds_read_b64_tr_b16 v[124:125], v201 offset:38080
	ds_read_b64_tr_b16 v[126:127], v201 offset:40640
	v_add_f32_e32 v169, v169, v93
	v_add_f32_e32 v170, v170, v94
	v_add_f32_e32 v171, v171, v95
	v_add_f32_e32 v168, v168, v96
	v_add_f32_e32 v169, v169, v97
	s_waitcnt lgkmcnt(6)
	v_mfma_f32_32x32x16_bf16 v[48:63], v[112:115], v[156:159], v[48:63]
	ds_read_b64_tr_b16 v[112:113], v201 offset:43008
	ds_read_b64_tr_b16 v[114:115], v201 offset:45568
	v_add_f32_e32 v170, v170, v98
	v_add_f32_e32 v171, v171, v99
	v_add_f32_e32 v168, v168, v100
	v_add_f32_e32 v169, v169, v101
	v_add_f32_e32 v170, v170, v102
	s_waitcnt lgkmcnt(6)
	v_mfma_f32_32x32x16_bf16 v[32:47], v[116:119], v[156:159], v[32:47]
	ds_read_b64_tr_b16 v[116:117], v201 offset:43072
	ds_read_b64_tr_b16 v[118:119], v201 offset:45632
	v_add_f32_e32 v171, v171, v103
	v_add_f32_e32 v168, v168, v104
	v_add_f32_e32 v169, v169, v105
	v_add_f32_e32 v170, v170, v106
	v_add_f32_e32 v171, v171, v107
	s_waitcnt lgkmcnt(6)
	v_mfma_f32_32x32x16_bf16 v[16:31], v[120:123], v[156:159], v[16:31]
	ds_read_b64_tr_b16 v[120:121], v201 offset:43136
	ds_read_b64_tr_b16 v[122:123], v201 offset:45696
	v_add_f32_e32 v168, v168, v108
	v_add_f32_e32 v169, v169, v109
	v_add_f32_e32 v170, v170, v110
	v_add_f32_e32 v171, v171, v111
	v_add_f32_e32 v168, v168, v64
	s_waitcnt lgkmcnt(6)
	v_mfma_f32_32x32x16_bf16 v[0:15], v[124:127], v[156:159], v[0:15]
	ds_read_b64_tr_b16 v[124:125], v201 offset:43200
	ds_read_b64_tr_b16 v[126:127], v201 offset:45760
	v_add_f32_e32 v169, v169, v65
	v_add_f32_e32 v170, v170, v66
	v_add_f32_e32 v171, v171, v67
	v_add_f32_e32 v168, v168, v68
	v_add_f32_e32 v169, v169, v69
	s_waitcnt lgkmcnt(6)
	v_mfma_f32_32x32x16_bf16 v[48:63], v[112:115], v[160:163], v[48:63]
	ds_read_b64_tr_b16 v[112:113], v201 offset:48128
	ds_read_b64_tr_b16 v[114:115], v201 offset:50688
	v_add_f32_e32 v170, v170, v70
	v_add_f32_e32 v171, v171, v71
	v_add_f32_e32 v168, v168, v72
	v_add_f32_e32 v169, v169, v73
	v_add_f32_e32 v170, v170, v74
	s_waitcnt lgkmcnt(6)
	v_mfma_f32_32x32x16_bf16 v[32:47], v[116:119], v[160:163], v[32:47]
	ds_read_b64_tr_b16 v[116:117], v201 offset:48192
	ds_read_b64_tr_b16 v[118:119], v201 offset:50752
	v_add_f32_e32 v171, v171, v75
	v_add_f32_e32 v168, v168, v76
	v_add_f32_e32 v169, v169, v77
	v_add_f32_e32 v170, v170, v78
	v_add_f32_e32 v171, v171, v79
	s_waitcnt lgkmcnt(6)
	v_mfma_f32_32x32x16_bf16 v[16:31], v[120:123], v[160:163], v[16:31]
	ds_read_b64_tr_b16 v[120:121], v201 offset:48256
	ds_read_b64_tr_b16 v[122:123], v201 offset:50816
	s_waitcnt lgkmcnt(6)
	v_mfma_f32_32x32x16_bf16 v[0:15], v[124:127], v[160:163], v[0:15]
	ds_read_b64_tr_b16 v[124:125], v201 offset:48320
	ds_read_b64_tr_b16 v[126:127], v201 offset:50880
	s_waitcnt lgkmcnt(6)
	v_mfma_f32_32x32x16_bf16 v[48:63], v[112:115], v[164:167], v[48:63]
	s_waitcnt lgkmcnt(4)
	v_mfma_f32_32x32x16_bf16 v[32:47], v[116:119], v[164:167], v[32:47]
	s_waitcnt lgkmcnt(2)
	v_mfma_f32_32x32x16_bf16 v[16:31], v[120:123], v[164:167], v[16:31]
	s_waitcnt lgkmcnt(0)
	v_mfma_f32_32x32x16_bf16 v[0:15], v[124:127], v[164:167], v[0:15]
	s_cmp_lg_u32 s25, 0x100000
	s_mov_b32 s26, s25
	v_mov_b64_e32 v[64:65], v[128:129]
	v_mov_b64_e32 v[66:67], v[130:131]
	v_mov_b64_e32 v[68:69], v[132:133]
	v_mov_b64_e32 v[70:71], v[134:135]
	s_cbranch_scc0 .LBB0_1845
.LBB0_1825:
	s_waitcnt vmcnt(0)
	s_barrier
	s_add_i32 s25, s26, 0x10000
	v_mov_b64_e32 v[128:129], v[64:65]
	v_mov_b64_e32 v[130:131], v[66:67]
	v_mov_b64_e32 v[132:133], v[68:69]
	v_mov_b64_e32 v[134:135], v[70:71]
	s_branch .LBB0_1824

; #define LAS __attribute__((address_space(3)))
; #define MFMA32(a, b, c) __builtin_amdgcn_mfma_f32_32x32x16_bf16((a), (b), (c), 0, 0, 0)
; #define VTR_SET(lo, hi, c) do { _Pragma("unroll") for (int d = 0; d < ND; ++d) { \
;         VTR_ASM(lo[d], va, (32 * ((c) >> 1) + 16 * ((c) & 1)) * VSTR + d * 64); VTR_ASM(hi[d], va, (32 * ((c) >> 1) + 16 * ((c) & 1)) * VSTR + d * 64 + 8 * VSTR); } } while (0)
; #define VTR_SET(lo, hi, base, c) do { _Pragma("unroll") for (int d = 0; d < ND; ++d) { \
;         VTR_ASM(lo[d], base, (32 * ((c) >> 1) + 16 * ((c) & 1)) * VSTR + d * 64); VTR_ASM(hi[d], base, (32 * ((c) >> 1) + 16 * ((c) & 1)) * VSTR + d * 64 + 8 * VSTR); } } while (0)
; template <int DQK, int DV, int KSTR, int VSTR>
; DI void attn_step2(const LAS unsigned char* ta, const LAS unsigned char* tb, int koff, int voff, const bf16x8 (&qf)[DQK / 16], f32x16 (&o)[DV / 32], float& l0, float& l1, float& l2, float& l3) {
;     ...
;     for (int ks = 0; ks < NKS; ++ks) {
;         const bf16x8 k0 = *(const LAS bf16x8*)(ta + koff + ks * 32), k1 = *(const LAS bf16x8*)(ta + koff + 32 * KSTR + ks * 32);
;         sa[0] = MFMA32(k0, qf[ks], ks == 0 ? zero16 : sa[0]); sa[1] = MFMA32(k1, qf[ks], ks == 0 ? zero16 : sa[1]);
;     }
;     const unsigned va = (unsigned)(uintptr_t)(ta + voff), vb = (unsigned)(uintptr_t)(tb + voff);
;     s16x4 alo[ND], ahi[ND], blo[ND], bhi[ND];
;     ...
;     VTR_SET(alo, ahi, va, 0);
.LBB0_1888:
	s_and_b32 s10, s26, 0x10000
	v_add_u32_e32 v176, s10, v197
	v_add_u32_e32 v202, s10, v209
	v_add_u32_e32 v202, 0x2400, v202
	s_and_b32 s27, s25, 0x10000
	s_cmp_eq_u32 s26, 0xf0000
	s_cselect_b64 s[44:45], -1, 0
	ds_read_b128 v[212:215], v176
	ds_read_b128 v[216:219], v176 offset:32
	ds_read_b128 v[220:223], v176 offset:64
	ds_read_b128 v[224:227], v176 offset:96
	ds_read_b128 v[172:175], v176 offset:4608
	ds_read_b128 v[178:181], v176 offset:4640
	s_waitcnt lgkmcnt(5)
	v_mfma_f32_32x32x16_bf16 v[64:79], v[212:215], v[136:139], 0
	ds_read_b128 v[212:215], v176 offset:4672
	s_or_b64 s[10:11], s[44:45], s[0:1]
	s_cbranch_scc1 .Ldiff2_dma_skip_0
	s_add_i32 m0, s27, s22
	s_nop 0
	global_load_lds_dwordx4 v[128:129], off
	v_lshl_add_u64 v[128:129], v[128:129], 0, s[82:83]

; #define LAS __attribute__((address_space(3)))
; #define MFMA32(a, b, c) __builtin_amdgcn_mfma_f32_32x32x16_bf16((a), (b), (c), 0, 0, 0)
; #define VTR_SET(lo, hi, c) do { _Pragma("unroll") for (int d = 0; d < ND; ++d) { \
;         VTR_ASM(lo[d], va, (32 * ((c) >> 1) + 16 * ((c) & 1)) * VSTR + d * 64); VTR_ASM(hi[d], va, (32 * ((c) >> 1) + 16 * ((c) & 1)) * VSTR + d * 64 + 8 * VSTR); } } while (0)
; #define PV_MMA(lo, hi, c) do { _Pragma("unroll") for (int d = 0; d < ND; ++d) { const bf16x8 vf = __builtin_shufflevector(lo[d], hi[d], 0, 1, 2, 3, 4, 5, 6, 7); o[d] = MFMA32(vf, pf[(c) >> 1][(c) & 1], o[d]); } } while (0)
; #define VTR_SET(lo, hi, base, c) do { _Pragma("unroll") for (int d = 0; d < ND; ++d) { \
;         VTR_ASM(lo[d], base, (32 * ((c) >> 1) + 16 * ((c) & 1)) * VSTR + d * 64); VTR_ASM(hi[d], base, (32 * ((c) >> 1) + 16 * ((c) & 1)) * VSTR + d * 64 + 8 * VSTR); } } while (0)
; #define PV_MMA(lo, hi, pf_) do { _Pragma("unroll") for (int d = 0; d < ND; ++d) { const bf16x8 vf = __builtin_shufflevector(lo[d], hi[d], 0, 1, 2, 3, 4, 5, 6, 7); o[d] = MFMA32(vf, pf_, o[d]); } } while (0)
; template <int DQK, int DV, int KSTR, int VSTR>
; DI void attn_step2(const LAS unsigned char* ta, const LAS unsigned char* tb, int koff, int voff, const bf16x8 (&qf)[DQK / 16], f32x16 (&o)[DV / 32], float& l0, float& l1, float& l2, float& l3) {
;     ...
;     for (int c = 0; c < 4; ++c) {
; #pragma unroll
;         for (int ks = (c * NKS) / 4; ks < ((c + 1) * NKS) / 4; ++ks) {
;             const bf16x8 k0 = *(const LAS bf16x8*)(tb + koff + ks * 32), k1 = *(const LAS bf16x8*)(tb + koff + 32 * KSTR + ks * 32);
;             sb[0] = MFMA32(k0, qf[ks], ks == 0 ? zero16 : sb[0]); sb[1] = MFMA32(k1, qf[ks], ks == 0 ? zero16 : sb[1]);
;         }
;         SM_CHUNK(sa, pfa[c], c);
;     }
;     vtr_wait<ND>(alo, ahi); VTR_SET(blo, bhi, va, 1); PV_MMA(alo, ahi, pfa[0]); SM_CHUNK(sb, pfb[0], 0);
;     vtr_wait<ND>(blo, bhi); VTR_SET(alo, ahi, va, 2); PV_MMA(blo, bhi, pfa[1]); SM_CHUNK(sb, pfb[1], 1);
;     vtr_wait<ND>(alo, ahi); VTR_SET(blo, bhi, va, 3); PV_MMA(alo, ahi, pfa[2]); SM_CHUNK(sb, pfb[2], 2);
;     vtr_wait<ND>(blo, bhi); VTR_SET(alo, ahi, vb, 0); PV_MMA(blo, bhi, pfa[3]); SM_CHUNK(sb, pfb[3], 3);
.Ldiff2_dma_skip_6:
	v_exp_f32_e32 v67, v67
	v_exp_f32_e32 v68, v68
	v_exp_f32_e32 v69, v69
	s_waitcnt lgkmcnt(5)
	v_mfma_f32_32x32x16_bf16 v[80:95], v[216:219], v[148:151], v[80:95]
	ds_read_b128 v[216:219], v176 offset:37408
	ds_read_b64_tr_b16 v[112:113], v202
	ds_read_b64_tr_b16 v[114:115], v202 offset:2560
	s_orn2_b64 s[10:11], s[44:45], s[68:69]
	s_cbranch_scc1 .Ldiff2_dma_skip_7
	s_add_i32 s10, s27, s13
	s_add_i32 m0, s10, 0x8000
	s_nop 0
	global_load_lds_dwordx4 v[134:135], off
	v_lshl_add_u64 v[134:135], v[134:135], 0, s[82:83]
.Ldiff2_dma_skip_7:
	v_exp_f32_e32 v70, v70
	v_exp_f32_e32 v71, v71
	v_exp_f32_e32 v72, v72
	s_waitcnt lgkmcnt(7)
	v_mfma_f32_32x32x16_bf16 v[96:111], v[220:223], v[136:139], 0
	ds_read_b128 v[220:223], v176 offset:37440
	ds_read_b64_tr_b16 v[116:117], v202 offset:64
	ds_read_b64_tr_b16 v[118:119], v202 offset:2624
	v_exp_f32_e32 v73, v73
	v_exp_f32_e32 v74, v74
	v_exp_f32_e32 v75, v75
	s_waitcnt lgkmcnt(9)
	v_mfma_f32_32x32x16_bf16 v[96:111], v[224:227], v[140:143], v[96:111]
	ds_read_b128 v[224:227], v176 offset:37472
	ds_read_b64_tr_b16 v[120:121], v202 offset:128
	ds_read_b64_tr_b16 v[122:123], v202 offset:2688
	v_exp_f32_e32 v76, v76
	v_exp_f32_e32 v77, v77
	v_exp_f32_e32 v78, v78
	s_waitcnt lgkmcnt(11)
	v_mfma_f32_32x32x16_bf16 v[96:111], v[172:175], v[144:147], v[96:111]
	ds_read_b64_tr_b16 v[124:125], v202 offset:192
	ds_read_b64_tr_b16 v[126:127], v202 offset:2752
	v_exp_f32_e32 v79, v79
	v_cvt_pk_bf16_f32 v152, v64, v65
	v_cvt_pk_bf16_f32 v153, v66, v67
	v_cvt_pk_bf16_f32 v154, v68, v69
	v_cvt_pk_bf16_f32 v155, v70, v71
	s_waitcnt lgkmcnt(12)
	v_mfma_f32_32x32x16_bf16 v[96:111], v[178:181], v[148:151], v[96:111]
	v_cvt_pk_bf16_f32 v156, v72, v73
	v_cvt_pk_bf16_f32 v157, v74, v75
	v_cvt_pk_bf16_f32 v158, v76, v77
	v_cvt_pk_bf16_f32 v159, v78, v79
	v_exp_f32_e32 v80, v80
	s_waitcnt lgkmcnt(8)
	v_mfma_f32_32x32x16_bf16 v[0:15], v[112:115], v[152:155], v[0:15]
	ds_read_b64_tr_b16 v[112:113], v202 offset:5120
	ds_read_b64_tr_b16 v[114:115], v202 offset:7680
	v_exp_f32_e32 v81, v81
	v_exp_f32_e32 v82, v82
	v_exp_f32_e32 v83, v83
	s_waitcnt lgkmcnt(7)
	v_mfma_f32_32x32x16_bf16 v[48:63], v[116:119], v[152:155], v[48:63]
	ds_read_b64_tr_b16 v[116:117], v202 offset:5184
	ds_read_b64_tr_b16 v[118:119], v202 offset:7744
	v_exp_f32_e32 v84, v84
	v_exp_f32_e32 v85, v85
	v_exp_f32_e32 v86, v86
	s_waitcnt lgkmcnt(6)
	v_mfma_f32_32x32x16_bf16 v[32:47], v[120:123], v[152:155], v[32:47]
	ds_read_b64_tr_b16 v[120:121], v202 offset:5248
	ds_read_b64_tr_b16 v[122:123], v202 offset:7808
	v_exp_f32_e32 v87, v87
	v_exp_f32_e32 v88, v88
	v_exp_f32_e32 v89, v89
	s_waitcnt lgkmcnt(6)
	v_mfma_f32_32x32x16_bf16 v[16:31], v[124:127], v[152:155], v[16:31]
	ds_read_b64_tr_b16 v[124:125], v202 offset:5312
	ds_read_b64_tr_b16 v[126:127], v202 offset:7872
	v_exp_f32_e32 v90, v90
	v_exp_f32_e32 v91, v91
	v_exp_f32_e32 v92, v92
	s_waitcnt lgkmcnt(6)
	v_mfma_f32_32x32x16_bf16 v[0:15], v[112:115], v[156:159], v[0:15]
	ds_read_b64_tr_b16 v[112:113], v202 offset:10240
	ds_read_b64_tr_b16 v[114:115], v202 offset:12800
	v_exp_f32_e32 v93, v93
	v_exp_f32_e32 v94, v94
	v_exp_f32_e32 v95, v95
	s_waitcnt lgkmcnt(6)
	v_mfma_f32_32x32x16_bf16 v[48:63], v[116:119], v[156:159], v[48:63]
	ds_read_b64_tr_b16 v[116:117], v202 offset:10304
	ds_read_b64_tr_b16 v[118:119], v202 offset:12864
	v_cvt_pk_bf16_f32 v160, v80, v81
	v_cvt_pk_bf16_f32 v161, v82, v83
	v_cvt_pk_bf16_f32 v162, v84, v85
	v_cvt_pk_bf16_f32 v163, v86, v87
	v_cvt_pk_bf16_f32 v164, v88, v89
	v_cvt_pk_bf16_f32 v165, v90, v91
	s_waitcnt lgkmcnt(6)
	v_mfma_f32_32x32x16_bf16 v[32:47], v[120:123], v[156:159], v[32:47]
	ds_read_b64_tr_b16 v[120:121], v202 offset:10368
	ds_read_b64_tr_b16 v[122:123], v202 offset:12928
	v_cvt_pk_bf16_f32 v166, v92, v93
	v_cvt_pk_bf16_f32 v167, v94, v95
	v_exp_f32_e32 v96, v96
	v_exp_f32_e32 v97, v97
	s_waitcnt lgkmcnt(6)
	v_mfma_f32_32x32x16_bf16 v[16:31], v[124:127], v[156:159], v[16:31]
	ds_read_b64_tr_b16 v[124:125], v202 offset:10432
	ds_read_b64_tr_b16 v[126:127], v202 offset:12992
	v_exp_f32_e32 v98, v98
	v_exp_f32_e32 v99, v99
	v_exp_f32_e32 v100, v100
	v_add_f32_e32 v168, v168, v64
	v_add_f32_e32 v169, v169, v65
	v_add_f32_e32 v170, v170, v66
	v_add_f32_e32 v171, v171, v67
	v_add_f32_e32 v168, v168, v68
	v_add_f32_e32 v169, v169, v69
	v_add_f32_e32 v170, v170, v70
	v_add_f32_e32 v171, v171, v71
	v_add_f32_e32 v168, v168, v72
	v_add_f32_e32 v169, v169, v73
	v_add_f32_e32 v170, v170, v74
	v_add_f32_e32 v171, v171, v75
	v_add_f32_e32 v168, v168, v76
	v_add_f32_e32 v169, v169, v77
	v_add_f32_e32 v170, v170, v78
	v_add_f32_e32 v171, v171, v79
	v_mfma_f32_32x32x16_bf16 v[64:79], v[212:215], v[136:139], 0
	v_exp_f32_e32 v101, v101
	v_exp_f32_e32 v102, v102
	v_exp_f32_e32 v103, v103
	v_mfma_f32_32x32x16_bf16 v[64:79], v[216:219], v[140:143], v[64:79]
	v_exp_f32_e32 v104, v104
	v_exp_f32_e32 v105, v105
	v_exp_f32_e32 v106, v106
	v_mfma_f32_32x32x16_bf16 v[64:79], v[220:223], v[144:147], v[64:79]
	v_exp_f32_e32 v107, v107
	v_exp_f32_e32 v108, v108
	v_exp_f32_e32 v109, v109
	v_mfma_f32_32x32x16_bf16 v[64:79], v[224:227], v[148:151], v[64:79]
	v_exp_f32_e32 v110, v110
	v_exp_f32_e32 v111, v111
	v_cvt_pk_bf16_f32 v152, v96, v97
	s_waitcnt lgkmcnt(6)
	v_mfma_f32_32x32x16_bf16 v[0:15], v[112:115], v[160:163], v[0:15]
	ds_read_b64_tr_b16 v[112:113], v202 offset:15360
	ds_read_b64_tr_b16 v[114:115], v202 offset:17920
	v_cvt_pk_bf16_f32 v153, v98, v99
	v_cvt_pk_bf16_f32 v154, v100, v101
	v_cvt_pk_bf16_f32 v155, v102, v103
	v_cvt_pk_bf16_f32 v156, v104, v105
	v_cvt_pk_bf16_f32 v157, v106, v107
	s_waitcnt lgkmcnt(6)
; #define LAS __attribute__((address_space(3)))
; #define VTR_SET(lo, hi, c) do { _Pragma("unroll") for (int d = 0; d < ND; ++d) { \
;         VTR_ASM(lo[d], va, (32 * ((c) >> 1) + 16 * ((c) & 1)) * VSTR + d * 64); VTR_ASM(hi[d], va, (32 * ((c) >> 1) + 16 * ((c) & 1)) * VSTR + d * 64 + 8 * VSTR); } } while (0)
; #define PV_MMA(lo, hi, c) do { _Pragma("unroll") for (int d = 0; d < ND; ++d) { const bf16x8 vf = __builtin_shufflevector(lo[d], hi[d], 0, 1, 2, 3, 4, 5, 6, 7); o[d] = MFMA32(vf, pf[(c) >> 1][(c) & 1], o[d]); } } while (0)
; #define VTR_SET(lo, hi, base, c) do { _Pragma("unroll") for (int d = 0; d < ND; ++d) { \
;         VTR_ASM(lo[d], base, (32 * ((c) >> 1) + 16 * ((c) & 1)) * VSTR + d * 64); VTR_ASM(hi[d], base, (32 * ((c) >> 1) + 16 * ((c) & 1)) * VSTR + d * 64 + 8 * VSTR); } } while (0)
; #define PV_MMA(lo, hi, pf_) do { _Pragma("unroll") for (int d = 0; d < ND; ++d) { const bf16x8 vf = __builtin_shufflevector(lo[d], hi[d], 0, 1, 2, 3, 4, 5, 6, 7); o[d] = MFMA32(vf, pf_, o[d]); } } while (0)
; template <int DQK, int DV, int KSTR, int VSTR>
; DI void attn_step2(const LAS unsigned char* ta, const LAS unsigned char* tb, int koff, int voff, const bf16x8 (&qf)[DQK / 16], f32x16 (&o)[DV / 32], float& l0, float& l1, float& l2, float& l3) {
;     ...
;     vtr_wait<ND>(alo, ahi); VTR_SET(blo, bhi, va, 3); PV_MMA(alo, ahi, pfa[2]); SM_CHUNK(sb, pfb[2], 2);
;     vtr_wait<ND>(blo, bhi); VTR_SET(alo, ahi, vb, 0); PV_MMA(blo, bhi, pfa[3]); SM_CHUNK(sb, pfb[3], 3);
;     vtr_wait<ND>(alo, ahi); VTR_SET(blo, bhi, vb, 1); PV_MMA(alo, ahi, pfb[0]);
;     vtr_wait<ND>(blo, bhi); VTR_SET(alo, ahi, vb, 2); PV_MMA(blo, bhi, pfb[1]);
;     vtr_wait<ND>(alo, ahi); VTR_SET(blo, bhi, vb, 3); PV_MMA(alo, ahi, pfb[2]);
;     vtr_wait<ND>(blo, bhi); PV_MMA(blo, bhi, pfb[3]);
; template <int DQK, int DV, int kpitch, int vpitch>
; DI void attn_map(LAS unsigned char* lds, const bf16x8 (&qf)[DQK / 16], const bf16* Kg, const bf16* Vg, f32x16 (&o)[DV / 32], float& lsum, int tid, int lane) {
;     ...
;     for (int s = 0; s < NSTEP; ++s) {
;         asm volatile("s_waitcnt vmcnt(0)" ::: "memory");
;         __builtin_amdgcn_s_barrier();
;         asm volatile("" ::: "memory");
;         if (s + 1 < NSTEP) ATT_DMA2((s + 1) & 1);
;         const LAS unsigned char* ta = lds + (s & 1) * 2 * TILE;
;         attn_step2<DQK, DV, KSTR, VSTR>(ta, ta + TILE, koff, voff, qf, o, l0, l1, l2, l3);
;     }
	v_mfma_f32_32x32x16_bf16 v[48:63], v[116:119], v[160:163], v[48:63]
	ds_read_b64_tr_b16 v[116:117], v202 offset:15424
	ds_read_b64_tr_b16 v[118:119], v202 offset:17984
	v_cvt_pk_bf16_f32 v158, v108, v109
	v_cvt_pk_bf16_f32 v159, v110, v111
	v_exp_f32_e32 v64, v64
	v_exp_f32_e32 v65, v65
	s_waitcnt lgkmcnt(6)
	v_mfma_f32_32x32x16_bf16 v[32:47], v[120:123], v[160:163], v[32:47]
	ds_read_b64_tr_b16 v[120:121], v202 offset:15488
	ds_read_b64_tr_b16 v[122:123], v202 offset:18048
	v_exp_f32_e32 v66, v66
	v_exp_f32_e32 v67, v67
	v_exp_f32_e32 v68, v68
	s_waitcnt lgkmcnt(6)
	v_mfma_f32_32x32x16_bf16 v[16:31], v[124:127], v[160:163], v[16:31]
	ds_read_b64_tr_b16 v[124:125], v202 offset:15552
	ds_read_b64_tr_b16 v[126:127], v202 offset:18112
	v_exp_f32_e32 v69, v69
	v_exp_f32_e32 v70, v70
	v_exp_f32_e32 v71, v71
	s_waitcnt lgkmcnt(6)
	v_mfma_f32_32x32x16_bf16 v[0:15], v[112:115], v[164:167], v[0:15]
	ds_read_b64_tr_b16 v[112:113], v202 offset:32768
	ds_read_b64_tr_b16 v[114:115], v202 offset:35328
	v_exp_f32_e32 v72, v72
	v_exp_f32_e32 v73, v73
	v_exp_f32_e32 v74, v74
	s_waitcnt lgkmcnt(6)
	v_mfma_f32_32x32x16_bf16 v[48:63], v[116:119], v[164:167], v[48:63]
	ds_read_b64_tr_b16 v[116:117], v202 offset:32832
	ds_read_b64_tr_b16 v[118:119], v202 offset:35392
	v_exp_f32_e32 v75, v75
	v_exp_f32_e32 v76, v76
	v_exp_f32_e32 v77, v77
	s_waitcnt lgkmcnt(6)
	v_mfma_f32_32x32x16_bf16 v[32:47], v[120:123], v[164:167], v[32:47]
	ds_read_b64_tr_b16 v[120:121], v202 offset:32896
	ds_read_b64_tr_b16 v[122:123], v202 offset:35456
	v_exp_f32_e32 v78, v78
	v_exp_f32_e32 v79, v79
	v_cvt_pk_bf16_f32 v160, v64, v65
	s_waitcnt lgkmcnt(6)
	v_mfma_f32_32x32x16_bf16 v[16:31], v[124:127], v[164:167], v[16:31]
	ds_read_b64_tr_b16 v[124:125], v202 offset:32960
	ds_read_b64_tr_b16 v[126:127], v202 offset:35520
	v_cvt_pk_bf16_f32 v161, v66, v67
	v_cvt_pk_bf16_f32 v162, v68, v69
	v_cvt_pk_bf16_f32 v163, v70, v71
	v_cvt_pk_bf16_f32 v164, v72, v73
	v_cvt_pk_bf16_f32 v165, v74, v75
	s_waitcnt lgkmcnt(6)
	v_mfma_f32_32x32x16_bf16 v[0:15], v[112:115], v[152:155], v[0:15]
	ds_read_b64_tr_b16 v[112:113], v202 offset:37888
	ds_read_b64_tr_b16 v[114:115], v202 offset:40448
	v_cvt_pk_bf16_f32 v166, v76, v77
	v_cvt_pk_bf16_f32 v167, v78, v79
	v_add_f32_e32 v168, v168, v80
	v_add_f32_e32 v169, v169, v81
	v_add_f32_e32 v170, v170, v82
	s_waitcnt lgkmcnt(6)
	v_mfma_f32_32x32x16_bf16 v[48:63], v[116:119], v[152:155], v[48:63]
	ds_read_b64_tr_b16 v[116:117], v202 offset:37952
	ds_read_b64_tr_b16 v[118:119], v202 offset:40512
	v_add_f32_e32 v171, v171, v83
	v_add_f32_e32 v168, v168, v84
	v_add_f32_e32 v169, v169, v85
	v_add_f32_e32 v170, v170, v86
	v_add_f32_e32 v171, v171, v87
	s_waitcnt lgkmcnt(6)
	v_mfma_f32_32x32x16_bf16 v[32:47], v[120:123], v[152:155], v[32:47]
	ds_read_b64_tr_b16 v[120:121], v202 offset:38016
	ds_read_b64_tr_b16 v[122:123], v202 offset:40576
	v_add_f32_e32 v168, v168, v88
	v_add_f32_e32 v169, v169, v89
	v_add_f32_e32 v170, v170, v90
	v_add_f32_e32 v171, v171, v91
	v_add_f32_e32 v168, v168, v92
	s_waitcnt lgkmcnt(6)
	v_mfma_f32_32x32x16_bf16 v[16:31], v[124:127], v[152:155], v[16:31]
	ds_read_b64_tr_b16 v[124:125], v202 offset:38080
	ds_read_b64_tr_b16 v[126:127], v202 offset:40640
	v_add_f32_e32 v169, v169, v93
	v_add_f32_e32 v170, v170, v94
	v_add_f32_e32 v171, v171, v95
	v_add_f32_e32 v168, v168, v96
	v_add_f32_e32 v169, v169, v97
	s_waitcnt lgkmcnt(6)
	v_mfma_f32_32x32x16_bf16 v[0:15], v[112:115], v[156:159], v[0:15]
	ds_read_b64_tr_b16 v[112:113], v202 offset:43008
	ds_read_b64_tr_b16 v[114:115], v202 offset:45568
	v_add_f32_e32 v170, v170, v98
	v_add_f32_e32 v171, v171, v99
	v_add_f32_e32 v168, v168, v100
	v_add_f32_e32 v169, v169, v101
	v_add_f32_e32 v170, v170, v102
	s_waitcnt lgkmcnt(6)
	v_mfma_f32_32x32x16_bf16 v[48:63], v[116:119], v[156:159], v[48:63]
	ds_read_b64_tr_b16 v[116:117], v202 offset:43072
	ds_read_b64_tr_b16 v[118:119], v202 offset:45632
	v_add_f32_e32 v171, v171, v103
	v_add_f32_e32 v168, v168, v104
	v_add_f32_e32 v169, v169, v105
	v_add_f32_e32 v170, v170, v106
	v_add_f32_e32 v171, v171, v107
	s_waitcnt lgkmcnt(6)
	v_mfma_f32_32x32x16_bf16 v[32:47], v[120:123], v[156:159], v[32:47]
	ds_read_b64_tr_b16 v[120:121], v202 offset:43136
	ds_read_b64_tr_b16 v[122:123], v202 offset:45696
	v_add_f32_e32 v168, v168, v108
	v_add_f32_e32 v169, v169, v109
	v_add_f32_e32 v170, v170, v110
	v_add_f32_e32 v171, v171, v111
	v_add_f32_e32 v168, v168, v64
	s_waitcnt lgkmcnt(6)
	v_mfma_f32_32x32x16_bf16 v[16:31], v[124:127], v[156:159], v[16:31]
	ds_read_b64_tr_b16 v[124:125], v202 offset:43200
	ds_read_b64_tr_b16 v[126:127], v202 offset:45760
	v_add_f32_e32 v169, v169, v65
	v_add_f32_e32 v170, v170, v66
	v_add_f32_e32 v171, v171, v67
	v_add_f32_e32 v168, v168, v68
	v_add_f32_e32 v169, v169, v69
	s_waitcnt lgkmcnt(6)
	v_mfma_f32_32x32x16_bf16 v[0:15], v[112:115], v[160:163], v[0:15]
	ds_read_b64_tr_b16 v[112:113], v202 offset:48128
	ds_read_b64_tr_b16 v[114:115], v202 offset:50688
	v_add_f32_e32 v170, v170, v70
	v_add_f32_e32 v171, v171, v71
	v_add_f32_e32 v168, v168, v72
	v_add_f32_e32 v169, v169, v73
	v_add_f32_e32 v170, v170, v74
	s_waitcnt lgkmcnt(6)
	v_mfma_f32_32x32x16_bf16 v[48:63], v[116:119], v[160:163], v[48:63]
	ds_read_b64_tr_b16 v[116:117], v202 offset:48192
	ds_read_b64_tr_b16 v[118:119], v202 offset:50752
	v_add_f32_e32 v171, v171, v75
	v_add_f32_e32 v168, v168, v76
	v_add_f32_e32 v169, v169, v77
	v_add_f32_e32 v170, v170, v78
	v_add_f32_e32 v171, v171, v79
	s_waitcnt lgkmcnt(6)
	v_mfma_f32_32x32x16_bf16 v[32:47], v[120:123], v[160:163], v[32:47]
	ds_read_b64_tr_b16 v[120:121], v202 offset:48256
	ds_read_b64_tr_b16 v[122:123], v202 offset:50816
	s_waitcnt lgkmcnt(6)
	v_mfma_f32_32x32x16_bf16 v[16:31], v[124:127], v[160:163], v[16:31]
	ds_read_b64_tr_b16 v[124:125], v202 offset:48320
	ds_read_b64_tr_b16 v[126:127], v202 offset:50880
	s_waitcnt lgkmcnt(6)
	v_mfma_f32_32x32x16_bf16 v[0:15], v[112:115], v[164:167], v[0:15]
	s_waitcnt lgkmcnt(4)
	v_mfma_f32_32x32x16_bf16 v[48:63], v[116:119], v[164:167], v[48:63]
	s_waitcnt lgkmcnt(2)
	v_mfma_f32_32x32x16_bf16 v[32:47], v[120:123], v[164:167], v[32:47]
	s_waitcnt lgkmcnt(0)
	v_mfma_f32_32x32x16_bf16 v[16:31], v[124:127], v[164:167], v[16:31]
	s_cmp_lg_u32 s25, 0x100000
	s_mov_b32 s26, s25
	v_mov_b64_e32 v[64:65], v[128:129]
	v_mov_b64_e32 v[66:67], v[130:131]
	v_mov_b64_e32 v[68:69], v[132:133]
	v_mov_b64_e32 v[70:71], v[134:135]
	s_cbranch_scc0 .LBB0_1780
